# m26 + step A: the next iteration's q fragments for heads 0-2 are read at the end of the current iteration (they are loop invariant), so the loop head no longer waits on LDS
# speedup vs baseline: 1.0016x; 1.0016x over previous
.Lidx_pw0:
	v_cndmask_b32_e64 v19, 0, 1, s[78:79]
	v_cmp_ne_u32_e64 s[28:29], 1, v19
	s_andn2_b64 vcc, exec, s[78:79]
	v_lshlrev_b32_e32 v39, 4, v36
	v_lshlrev_b32_e32 v172, 2, v167
	v_lshl_add_u32 v40, v167, 13, 0
	v_lshl_add_u32 v41, v18, 2, s14
	s_waitcnt lgkmcnt(0)
	s_barrier
	s_cbranch_vccnz .LBB0_1383
	s_add_i32 s0, s77, 8
	s_lshr_b32 s1, s0, 29
	s_add_i32 s0, s0, s1
	s_ashr_i32 s13, s0, 3
	s_add_i32 s0, 0, 0x22200
	v_add_u32_e32 v173, s0, v39
	v_readlane_b32 s0, v251, 29
	s_add_i32 s14, s13, -2
	s_add_i32 s15, s13, -3
	v_add_u32_e32 v174, s0, v39
	s_max_i32 s0, s13, 2
	s_lshl_b32 s0, s0, 3
	s_add_i32 s0, s0, -8
	s_and_b32 s16, s0, -16
	v_or_b32_e32 v175, s24, v167
	s_add_i32 s16, s16, 16
	s_mov_b32 s17, 0
	v_mov_b64_e32 v[42:43], 0
	v_mov_b64_e32 v[44:45], 0
	v_mov_b64_e32 v[46:47], 0
	v_mov_b64_e32 v[48:49], 0
	v_mov_b64_e32 v[50:51], 0
	v_mov_b64_e32 v[52:53], 0
	v_mov_b64_e32 v[54:55], 0
	v_mov_b64_e32 v[56:57], 0
	v_mov_b64_e32 v[58:59], 0
	v_mov_b64_e32 v[60:61], 0
	v_mov_b64_e32 v[62:63], 0
	v_mov_b64_e32 v[64:65], 0
	v_mov_b64_e32 v[66:67], 0
	v_mov_b64_e32 v[68:69], 0
	v_mov_b64_e32 v[70:71], 0
	v_mov_b64_e32 v[72:73], 0
	v_mov_b64_e32 v[74:75], 0
	v_mov_b64_e32 v[76:77], 0
	v_mov_b64_e32 v[78:79], 0
	v_mov_b64_e32 v[80:81], 0
	v_mov_b64_e32 v[82:83], 0
	v_mov_b64_e32 v[84:85], 0
	v_mov_b64_e32 v[86:87], 0
	v_mov_b64_e32 v[88:89], 0
	v_mov_b64_e32 v[90:91], 0
	v_mov_b64_e32 v[92:93], 0
	v_mov_b64_e32 v[94:95], 0
	v_mov_b64_e32 v[96:97], 0
	v_mov_b64_e32 v[98:99], 0
	v_mov_b64_e32 v[100:101], 0
	v_mov_b64_e32 v[102:103], 0
	v_mov_b64_e32 v[104:105], 0
	v_mov_b64_e32 v[106:107], 0
	v_mov_b64_e32 v[108:109], 0
	v_mov_b64_e32 v[110:111], 0
	v_mov_b64_e32 v[112:113], 0
	v_mov_b64_e32 v[114:115], 0
	v_mov_b32_e32 v117, 0
	v_mov_b64_e32 v[118:119], 0
	v_mov_b64_e32 v[120:121], 0
	v_mov_b64_e32 v[122:123], 0
	v_mov_b64_e32 v[124:125], 0
	v_mov_b64_e32 v[126:127], 0
	v_mov_b64_e32 v[128:129], 0
	v_mov_b64_e32 v[130:131], 0
	v_mov_b64_e32 v[132:133], 0
	v_mov_b64_e32 v[134:135], 0
	v_mov_b64_e32 v[136:137], 0
	v_mov_b64_e32 v[138:139], 0
	v_mov_b64_e32 v[140:141], 0
	v_mov_b64_e32 v[142:143], 0
	v_mov_b64_e32 v[144:145], 0
	v_mov_b64_e32 v[146:147], 0
	v_mov_b64_e32 v[148:149], 0
	v_mov_b64_e32 v[150:151], 0
	v_mov_b64_e32 v[152:153], 0
	v_mov_b64_e32 v[154:155], 0
	v_mov_b64_e32 v[156:157], 0
	v_mov_b64_e32 v[158:159], 0
	v_mov_b64_e32 v[160:161], 0
	v_mov_b64_e32 v[162:163], 0
	v_mov_b64_e32 v[164:165], 0
	v_mov_b32_e32 v166, 0
	v_mov_b64_e32 v[168:169], 0
	v_mov_b64_e32 v[170:171], 0
	v_mov_b32_e32 v176, v41
	s_mov_b32 s18, 0
	s_mov_b32 s19, 0
	ds_read_b128 v[200:203], v173
	ds_read_b128 v[204:207], v173 offset:1024
	ds_read_b128 v[208:211], v173 offset:2048
	ds_read_b128 v[212:215], v173 offset:3072
	ds_read_b128 v[216:219], v173 offset:4096
	ds_read_b128 v[226:229], v173 offset:5120
	v_lshlrev_b32_e32 v246, 21, v172
	s_branch .LBB0_1296

.LBB0_1296:
	s_add_i32 s8, s3, s17
	s_add_i32 s0, s18, 1
	s_add_i32 s9, s8, 8
	s_cmp_lt_i32 s0, s13
	s_cselect_b64 s[0:1], -1, 0
	s_and_b64 vcc, s[0:1], exec
	s_cselect_b32 s10, s9, s8
	s_add_i32 s9, s8, 16
	s_cmp_lt_i32 s18, s14
	s_cselect_b32 s9, s9, s8
	s_add_i32 s8, s8, 24
	s_cmp_lt_i32 s18, s15
	s_cselect_b32 s11, s8, s9
	s_lshl_b32 s68, s9, 4
	s_lshl_b64 s[8:9], s[68:69], 7
	ds_read_b128 v[22:25], v174
	ds_read_b128 v[18:21], v174 offset:1024
	s_waitcnt vmcnt(0) lgkmcnt(2)
	v_mfma_f32_16x16x32_bf16 v[230:233], v[6:9], v[200:203], 0
	ds_read_b128 v[178:181], v173 offset:6144
	ds_read_b128 v[182:185], v173 offset:7168
	v_mfma_f32_16x16x32_bf16 v[234:237], v[14:17], v[200:203], 0
	v_mfma_f32_16x16x32_bf16 v[230:233], v[2:5], v[204:207], v[230:233]
	s_nop 3
	v_mfma_f32_16x16x32_bf16 v[234:237], v[10:13], v[204:207], v[234:237]
	s_waitcnt lgkmcnt(2)
	v_mfma_f32_16x16x32_bf16 v[238:241], v[6:9], v[208:211], 0
	ds_read_b128 v[200:203], v173 offset:8192
	ds_read_b128 v[204:207], v173 offset:9216
	v_max_i32_e32 v250, 0, v230
	v_fma_f32 v34, v250, v22, 0
	v_max_i32_e32 v225, 0, v231
	v_fma_f32 v35, v225, v22, 0
	v_mfma_f32_16x16x32_bf16 v[242:245], v[14:17], v[208:211], 0
	v_max_i32_e32 v250, 0, v232
	v_fma_f32 v32, v250, v22, 0
	v_max_i32_e32 v225, 0, v233
	v_fma_f32 v33, v225, v22, 0
	v_mfma_f32_16x16x32_bf16 v[238:241], v[2:5], v[212:215], v[238:241]
	v_max_i32_e32 v250, 0, v234
	v_fma_f32 v30, v250, v22, 0
	v_max_i32_e32 v225, 0, v235
	v_fma_f32 v31, v225, v22, 0
	v_mfma_f32_16x16x32_bf16 v[242:245], v[10:13], v[212:215], v[242:245]
	v_max_i32_e32 v250, 0, v236
	v_fma_f32 v28, v250, v22, 0
	v_max_i32_e32 v225, 0, v237
	v_fma_f32 v29, v225, v22, 0
	v_mfma_f32_16x16x32_bf16 v[230:233], v[6:9], v[216:219], 0
	ds_read_b128 v[208:211], v173 offset:10240
	ds_read_b128 v[212:215], v173 offset:11264
	v_max_i32_e32 v250, 0, v238
	v_fmac_f32_e32 v34, v250, v23
	v_max_i32_e32 v225, 0, v239
	v_fmac_f32_e32 v35, v225, v23
	v_mfma_f32_16x16x32_bf16 v[234:237], v[14:17], v[216:219], 0
	v_max_i32_e32 v250, 0, v240
	v_fmac_f32_e32 v32, v250, v23
	v_max_i32_e32 v225, 0, v241
	v_fmac_f32_e32 v33, v225, v23
	v_mfma_f32_16x16x32_bf16 v[230:233], v[2:5], v[226:229], v[230:233]
	v_max_i32_e32 v250, 0, v242
	v_fmac_f32_e32 v30, v250, v23
	v_max_i32_e32 v225, 0, v243
	v_fmac_f32_e32 v31, v225, v23
	v_mfma_f32_16x16x32_bf16 v[234:237], v[10:13], v[226:229], v[234:237]
	v_max_i32_e32 v250, 0, v244
	v_fmac_f32_e32 v28, v250, v23
	v_max_i32_e32 v225, 0, v245
	v_fmac_f32_e32 v29, v225, v23
	s_waitcnt lgkmcnt(4)
	v_mfma_f32_16x16x32_bf16 v[238:241], v[6:9], v[178:181], 0
	ds_read_b128 v[216:219], v173 offset:12288
	ds_read_b128 v[226:229], v173 offset:13312
	v_max_i32_e32 v250, 0, v230
	v_fmac_f32_e32 v34, v250, v24
	v_max_i32_e32 v225, 0, v231
	v_fmac_f32_e32 v35, v225, v24
	v_mfma_f32_16x16x32_bf16 v[242:245], v[14:17], v[178:181], 0
	v_max_i32_e32 v250, 0, v232
	v_fmac_f32_e32 v32, v250, v24
	v_max_i32_e32 v225, 0, v233
	v_fmac_f32_e32 v33, v225, v24
	v_mfma_f32_16x16x32_bf16 v[238:241], v[2:5], v[182:185], v[238:241]
	v_max_i32_e32 v250, 0, v234
	v_fmac_f32_e32 v30, v250, v24
	v_max_i32_e32 v225, 0, v235
	v_fmac_f32_e32 v31, v225, v24
	v_mfma_f32_16x16x32_bf16 v[242:245], v[10:13], v[182:185], v[242:245]
	v_max_i32_e32 v250, 0, v236
	v_fmac_f32_e32 v28, v250, v24
	v_max_i32_e32 v225, 0, v237
	v_fmac_f32_e32 v29, v225, v24
	s_waitcnt lgkmcnt(4)
	v_mfma_f32_16x16x32_bf16 v[230:233], v[6:9], v[200:203], 0
	ds_read_b128 v[178:181], v173 offset:14336
	ds_read_b128 v[182:185], v173 offset:15360
	v_max_i32_e32 v250, 0, v238
	v_fmac_f32_e32 v34, v250, v25
	v_max_i32_e32 v225, 0, v239
	v_fmac_f32_e32 v35, v225, v25
	v_mfma_f32_16x16x32_bf16 v[234:237], v[14:17], v[200:203], 0
	v_max_i32_e32 v250, 0, v240
	v_fmac_f32_e32 v32, v250, v25
	v_max_i32_e32 v225, 0, v241
	v_fmac_f32_e32 v33, v225, v25
	v_mfma_f32_16x16x32_bf16 v[230:233], v[2:5], v[204:207], v[230:233]
	v_max_i32_e32 v250, 0, v242
	v_fmac_f32_e32 v30, v250, v25
	v_max_i32_e32 v225, 0, v243
	v_fmac_f32_e32 v31, v225, v25
	v_mfma_f32_16x16x32_bf16 v[234:237], v[10:13], v[204:207], v[234:237]
	v_max_i32_e32 v250, 0, v244
	v_fmac_f32_e32 v28, v250, v25
	v_max_i32_e32 v225, 0, v245
	v_fmac_f32_e32 v29, v225, v25
	s_waitcnt lgkmcnt(4)
	v_mfma_f32_16x16x32_bf16 v[238:241], v[6:9], v[208:211], 0
	v_max_i32_e32 v250, 0, v230
	v_fmac_f32_e32 v34, v250, v18
	v_max_i32_e32 v225, 0, v231
	v_fmac_f32_e32 v35, v225, v18
	v_mfma_f32_16x16x32_bf16 v[242:245], v[14:17], v[208:211], 0
	v_max_i32_e32 v250, 0, v232
	v_fmac_f32_e32 v32, v250, v18
	v_max_i32_e32 v225, 0, v233
	v_fmac_f32_e32 v33, v225, v18
	v_mfma_f32_16x16x32_bf16 v[238:241], v[2:5], v[212:215], v[238:241]
	v_max_i32_e32 v250, 0, v234
	v_fmac_f32_e32 v30, v250, v18
	v_max_i32_e32 v225, 0, v235
	v_fmac_f32_e32 v31, v225, v18
	v_mfma_f32_16x16x32_bf16 v[242:245], v[10:13], v[212:215], v[242:245]
	v_max_i32_e32 v250, 0, v236
	v_fmac_f32_e32 v28, v250, v18
	v_max_i32_e32 v225, 0, v237
	v_fmac_f32_e32 v29, v225, v18
	s_waitcnt lgkmcnt(2)
	v_mfma_f32_16x16x32_bf16 v[230:233], v[6:9], v[216:219], 0
	v_max_i32_e32 v250, 0, v238
	v_fmac_f32_e32 v34, v250, v19
	v_max_i32_e32 v225, 0, v239
	v_fmac_f32_e32 v35, v225, v19
	v_mfma_f32_16x16x32_bf16 v[234:237], v[14:17], v[216:219], 0
	v_max_i32_e32 v250, 0, v240
	v_fmac_f32_e32 v32, v250, v19
	v_max_i32_e32 v225, 0, v241
	v_fmac_f32_e32 v33, v225, v19
	v_mfma_f32_16x16x32_bf16 v[230:233], v[2:5], v[226:229], v[230:233]
	v_max_i32_e32 v250, 0, v242
	v_fmac_f32_e32 v30, v250, v19
	v_max_i32_e32 v225, 0, v243
	v_fmac_f32_e32 v31, v225, v19
	v_mfma_f32_16x16x32_bf16 v[234:237], v[10:13], v[226:229], v[234:237]
	v_max_i32_e32 v250, 0, v244
	v_fmac_f32_e32 v28, v250, v19
	v_max_i32_e32 v225, 0, v245
	v_fmac_f32_e32 v29, v225, v19
	s_waitcnt lgkmcnt(0)
	v_mfma_f32_16x16x32_bf16 v[238:241], v[6:9], v[178:181], 0
	ds_read_b128 v[200:203], v173
	ds_read_b128 v[204:207], v173 offset:1024
	ds_read_b128 v[208:211], v173 offset:2048
	ds_read_b128 v[212:215], v173 offset:3072
	ds_read_b128 v[216:219], v173 offset:4096
	ds_read_b128 v[226:229], v173 offset:5120
	v_max_i32_e32 v250, 0, v230
	v_fmac_f32_e32 v34, v250, v20
	v_max_i32_e32 v225, 0, v231
	v_fmac_f32_e32 v35, v225, v20
	v_mfma_f32_16x16x32_bf16 v[242:245], v[14:17], v[178:181], 0
	v_max_i32_e32 v250, 0, v232
	v_fmac_f32_e32 v32, v250, v20
	v_max_i32_e32 v225, 0, v233
	v_fmac_f32_e32 v33, v225, v20
	v_mfma_f32_16x16x32_bf16 v[238:241], v[2:5], v[182:185], v[238:241]
	v_max_i32_e32 v250, 0, v234
	v_fmac_f32_e32 v30, v250, v20
	v_max_i32_e32 v225, 0, v235
	v_fmac_f32_e32 v31, v225, v20
	v_mfma_f32_16x16x32_bf16 v[242:245], v[10:13], v[182:185], v[242:245]
	v_max_i32_e32 v250, 0, v236
	v_fmac_f32_e32 v28, v250, v20
	v_max_i32_e32 v225, 0, v237
	v_fmac_f32_e32 v29, v225, v20
	v_max_i32_e32 v250, 0, v238
	v_fmac_f32_e32 v34, v250, v21
	v_max_i32_e32 v225, 0, v239
	v_fmac_f32_e32 v35, v225, v21
	v_max_i32_e32 v250, 0, v240
	v_fmac_f32_e32 v32, v250, v21
	v_max_i32_e32 v225, 0, v241
	v_fmac_f32_e32 v33, v225, v21
	v_max_i32_e32 v250, 0, v242
	v_fmac_f32_e32 v30, v250, v21
	v_max_i32_e32 v225, 0, v243
	v_fmac_f32_e32 v31, v225, v21
	v_max_i32_e32 v250, 0, v244
	v_fmac_f32_e32 v28, v250, v21
	v_max_i32_e32 v225, 0, v245
	v_fmac_f32_e32 v29, v225, v21
	v_lshl_add_u64 v[2:3], v[26:27], 0, s[8:9]
	s_lshl_b32 s8, s11, 4
	s_ashr_i32 s9, s8, 31
	s_lshl_b64 s[8:9], s[8:9], 7
	v_lshl_add_u64 v[10:11], v[26:27], 0, s[8:9]
	global_load_dwordx4 v[6:9], v[2:3], off
	s_nop 0
	global_load_dwordx4 v[2:5], v[2:3], off offset:64
	s_nop 0
	global_load_dwordx4 v[14:17], v[10:11], off
	s_nop 0
	global_load_dwordx4 v[10:13], v[10:11], off offset:64
	s_cmp_eq_u32 s10, s12
	v_ashrrev_i32_e32 v178, 31, v34
	s_cbranch_scc1 .LBB0_1317
	v_bitop3_b32 v18, v178, v34, s76 bitop3:0x36
	v_add_u32_e32 v19, v246, v18
	v_lshrrev_b32_e32 v20, 21, v19
	v_lshrrev_b32_e32 v19, 3, v20
	v_bitop3_b32 v19, v19, v20, 28 bitop3:0x6c
	v_lshl_add_u32 v19, v19, 2, v40
	ds_add_u32 v19, v186
	v_ashrrev_i32_e32 v19, 31, v35
	v_bitop3_b32 v19, v19, v35, s76 bitop3:0x36
	v_add_u32_e32 v20, v246, v19
	v_lshrrev_b32_e32 v21, 21, v20
	v_lshrrev_b32_e32 v20, 3, v21
	v_bitop3_b32 v20, v20, v21, 28 bitop3:0x6c
	v_lshl_add_u32 v20, v20, 2, v40
	ds_add_u32 v20, v186
	v_ashrrev_i32_e32 v20, 31, v32
	v_bitop3_b32 v20, v20, v32, s76 bitop3:0x36
	v_add_u32_e32 v21, v246, v20
	v_lshrrev_b32_e32 v22, 21, v21
	v_lshrrev_b32_e32 v21, 3, v22
	v_bitop3_b32 v21, v21, v22, 28 bitop3:0x6c
	v_lshl_add_u32 v21, v21, 2, v40
	ds_add_u32 v21, v186
	v_ashrrev_i32_e32 v21, 31, v33
	v_bitop3_b32 v23, v21, v33, s76 bitop3:0x36
	v_add_u32_e32 v21, v246, v23
	v_lshrrev_b32_e32 v22, 21, v21
	v_lshrrev_b32_e32 v21, 3, v22
	v_bitop3_b32 v21, v21, v22, 28 bitop3:0x6c
	v_lshl_add_u32 v21, v21, 2, v40
	ds_add_u32 v21, v186
	s_mov_b64 s[10:11], 0
	v_mov_b32_e32 v25, 0
	v_mov_b32_e32 v24, 0
	v_mov_b32_e32 v22, 0
	v_mov_b32_e32 v21, 0
	s_mov_b64 s[8:9], 0
	s_mov_b64 vcc, vcc
	s_cbranch_vccz .LBB0_1299
	v_ashrrev_i32_e32 v21, 31, v30
	v_bitop3_b32 v21, v21, v30, s76 bitop3:0x36
	v_add_u32_e32 v22, v246, v21
	v_lshrrev_b32_e32 v24, 21, v22
	v_lshrrev_b32_e32 v22, 3, v24
	v_bitop3_b32 v22, v22, v24, 28 bitop3:0x6c
	v_lshl_add_u32 v22, v22, 2, v40
	ds_add_u32 v22, v186
	v_ashrrev_i32_e32 v22, 31, v31
	v_bitop3_b32 v22, v22, v31, s76 bitop3:0x36
	v_add_u32_e32 v24, v246, v22
	v_lshrrev_b32_e32 v25, 21, v24
	v_lshrrev_b32_e32 v24, 3, v25
	v_bitop3_b32 v24, v24, v25, 28 bitop3:0x6c
	v_lshl_add_u32 v24, v24, 2, v40
	ds_add_u32 v24, v186
	v_ashrrev_i32_e32 v24, 31, v28
	v_bitop3_b32 v24, v24, v28, s76 bitop3:0x36
	v_add_u32_e32 v25, v246, v24
	v_lshrrev_b32_e32 v177, 21, v25
	v_lshrrev_b32_e32 v25, 3, v177
	v_bitop3_b32 v25, v25, v177, 28 bitop3:0x6c
	v_lshl_add_u32 v25, v25, 2, v40
	ds_add_u32 v25, v186
	v_ashrrev_i32_e32 v25, 31, v29
	v_bitop3_b32 v177, v25, v29, s76 bitop3:0x36
	s_mov_b64 s[8:9], -1
	v_mov_b32_e32 v25, v177
